# 2048 more layer-0 weight-transpose items (w_ffn1 tail, w_ffn3 head) moved from prep to the CUs idle during layer-0's small-GEMM phase; each prep wave now does one transpose item
# speedup vs baseline: 1.0055x; 1.0003x over previous
; __device__ __forceinline__ void prep_phase(const Params& p, LAS unsigned char* lds) {
;     ...
;         for (int it = gw; it < 2 * I_L; it += NGW) {
;             const int l = it / I_L; int r = it % I_L;
;             if (r < I_IN) { const int kb = r / 72, nb = r % 72; if (nb >= 48 && nb < 56) continue;
;                 transpose_item(p.w_in + (size_t)l * DM * INW_SRC, INW_SRC, DM, (bf16_t*)(ws + WS_WIN) + (size_t)l * INW * DM, 1, scr, kb, nb, lane); continue; }
;             r -= I_IN;
;             if (r < I_OUT) { transpose_item(p.w_out + (size_t)l * DM * DM, DM, DM, (bf16_t*)(ws + WS_WOUT) + (size_t)l * DM * DM, 0, scr, r / 32, r % 32, lane); continue; }
;             r -= I_OUT;
;             if (r < I_F1) { transpose_item(p.w_ffn1 + (size_t)l * DM * DFF, DFF, DM, (bf16_t*)(ws + WS_W13) + (size_t)l * N13 * DM, 2, scr, r / 88, r % 88, lane); continue; }
;             r -= I_F1;
;             if (r < I_F1) { transpose_item(p.w_ffn3 + (size_t)l * DM * DFF, DFF, DM, (bf16_t*)(ws + WS_W13) + (size_t)l * N13 * DM, 3, scr, r / 88, r % 88, lane); continue; }
;             r -= I_F1;
;             transpose_item(p.w_ffn2 + (size_t)l * DFF * DM, DM, DFF, (bf16_t*)(ws + WS_W2) + (size_t)l * DM * DFF, 0, scr, r / 32, r % 32, lane);
;         }
.LBB0_33:
	s_or_b64 exec, exec, s[14:15]
	v_add_u32_e32 v33, s80, v33
	s_movk_i32 s12, 0x7ff
	v_cmp_lt_i32_e32 vcc, s12, v33
	s_or_b64 s[10:11], vcc, s[10:11]
	s_andn2_b64 exec, exec, s[10:11]
	s_cbranch_execz .LBB0_76

; #define LAS __attribute__((address_space(3)))
; __device__ __forceinline__ void prep_phase(const Params& p, LAS unsigned char* lds) {
;     ...
;         LAS float* scr = (LAS float*)(lds + wave * 8448);
;         constexpr int I_IN = 16 * 72, I_OUT = 16 * 32, I_F1 = 16 * 88, I_F2 = 44 * 32, I_L = I_IN + I_OUT + 2 * I_F1 + I_F2;
;         for (int it = gw; it < 2 * I_L; it += NGW) {
.LBB0_858:
	s_cmp_lg_u32 s72, 0
	s_cbranch_scc1 .Lt5_skip
	s_cmp_lt_u32 s2, 0x90
	s_cbranch_scc1 .Lt5_skip
	v_writelane_b32 v250, s3, 0
	v_writelane_b32 v250, s12, 1
	v_writelane_b32 v250, s13, 2
	v_writelane_b32 v250, s14, 3
	v_writelane_b32 v250, s16, 4
	v_writelane_b32 v250, s17, 5
	v_writelane_b32 v250, s18, 6
	v_writelane_b32 v250, s19, 7
	v_writelane_b32 v250, s21, 8
	v_writelane_b32 v250, s22, 9
	v_writelane_b32 v250, s23, 10
	v_writelane_b32 v250, s26, 11
	v_writelane_b32 v250, s27, 12
	v_writelane_b32 v250, s28, 13
	v_writelane_b32 v250, s29, 14
	v_writelane_b32 v250, s30, 15
	v_writelane_b32 v250, s33, 16
	v_writelane_b32 v250, s34, 17
	v_writelane_b32 v250, s35, 18
	v_writelane_b32 v250, s36, 19
	v_writelane_b32 v250, s37, 20
	v_writelane_b32 v250, s43, 21
	v_writelane_b32 v250, s44, 22
	v_writelane_b32 v250, s45, 23
	v_writelane_b32 v250, s46, 24
	v_writelane_b32 v250, s47, 25
	v_writelane_b32 v250, s48, 26
	v_writelane_b32 v250, s49, 27
	v_writelane_b32 v250, s50, 28
	v_writelane_b32 v250, s51, 29
	v_writelane_b32 v250, s52, 30
	v_writelane_b32 v250, s53, 31
	v_writelane_b32 v250, s54, 32
	v_writelane_b32 v250, s55, 33
	v_writelane_b32 v250, s56, 34
	v_writelane_b32 v250, s57, 35
	v_writelane_b32 v250, s64, 36
	v_writelane_b32 v250, s66, 37
	v_writelane_b32 v250, s67, 38
	v_writelane_b32 v250, s72, 39
	v_writelane_b32 v250, s73, 40
	v_writelane_b32 v250, s76, 41
	v_writelane_b32 v250, s80, 42
	v_writelane_b32 v250, s81, 43
	v_writelane_b32 v250, s84, 44
	v_writelane_b32 v250, s88, 45
	v_writelane_b32 v250, s89, 46
	v_writelane_b32 v250, s90, 47
	v_writelane_b32 v250, vcc_lo, 48
	v_writelane_b32 v250, vcc_hi, 49
	v_writelane_b32 v250, exec_lo, 50
	v_writelane_b32 v250, exec_hi, 51
	s_mov_b64 exec, -1
	v_mov_b32_e32 v66, v192
	v_lshrrev_b32_e32 v11, 6, v66
	v_and_b32_e32 v67, 63, v66
	v_lshlrev_b32_e32 v81, 2, v67
	s_sub_u32 s0, s2, 0x90
	s_lshl_b32 s0, s0, 3
	v_add_u32_e32 v80, s0, v11
	v_add_u32_e32 v80, 0x800, v80
	s_movk_i32 s80, 0x380

; #define LAS __attribute__((address_space(3)))
; __device__ __forceinline__ void prep_phase(const Params& p, LAS unsigned char* lds) {
;     ...
;         LAS float* scr = (LAS float*)(lds + wave * 8448);
;         constexpr int I_IN = 16 * 72, I_OUT = 16 * 32, I_F1 = 16 * 88, I_F2 = 44 * 32, I_L = I_IN + I_OUT + 2 * I_F1 + I_F2;
;         for (int it = gw; it < 2 * I_L; it += NGW) {
;             const int l = it / I_L; int r = it % I_L;
;             if (r < I_IN) { const int kb = r / 72, nb = r % 72; if (nb >= 48 && nb < 56) continue;
;                 transpose_item(p.w_in + (size_t)l * DM * INW_SRC, INW_SRC, DM, (bf16_t*)(ws + WS_WIN) + (size_t)l * INW * DM, 1, scr, kb, nb, lane); continue; }
;             r -= I_IN;
;             if (r < I_OUT) { transpose_item(p.w_out + (size_t)l * DM * DM, DM, DM, (bf16_t*)(ws + WS_WOUT) + (size_t)l * DM * DM, 0, scr, r / 32, r % 32, lane); continue; }
;             r -= I_OUT;
;             if (r < I_F1) { transpose_item(p.w_ffn1 + (size_t)l * DM * DFF, DFF, DM, (bf16_t*)(ws + WS_W13) + (size_t)l * N13 * DM, 2, scr, r / 88, r % 88, lane); continue; }
;             r -= I_F1;
;             if (r < I_F1) { transpose_item(p.w_ffn3 + (size_t)l * DM * DFF, DFF, DM, (bf16_t*)(ws + WS_W13) + (size_t)l * N13 * DM, 3, scr, r / 88, r % 88, lane); continue; }
;             r -= I_F1;
;             transpose_item(p.w_ffn2 + (size_t)l * DFF * DM, DM, DFF, (bf16_t*)(ws + WS_W2) + (size_t)l * DM * DFF, 0, scr, r / 32, r % 32, lane);
	v_readlane_b32 s4, v252, 0
	v_readlane_b32 s8, v252, 4
	v_readlane_b32 s5, v252, 1
	v_readlane_b32 s9, v252, 5
	s_add_u32 s4, s8, 0x2400000
	v_readlane_b32 s6, v252, 2
	s_addc_u32 s5, s9, 0
	s_movk_i32 s3, 0x2100
	v_readlane_b32 s7, v252, 3
	v_lshlrev_b32_e32 v3, 3, v67
	s_add_u32 s6, s8, 0xe00000
	v_mul_lo_u32 v1, v11, s3
	v_lshrrev_b32_e32 v13, 3, v67
	v_and_b32_e32 v12, 56, v3
	s_addc_u32 s7, s9, 0
	v_add_u32_e32 v1, 0, v1
	v_readlane_b32 s10, v252, 6
	v_readlane_b32 s11, v252, 7
	v_lshrrev_b32_e32 v6, 5, v67
	v_and_b32_e32 v2, 31, v66
	v_mul_u32_u24_e32 v3, 0x84, v12
	v_lshlrev_b32_e32 v4, 2, v13
	s_add_u32 s8, s8, 0xa00000
	v_mov_b32_e32 v9, 0
	v_lshl_add_u32 v10, v2, 2, v1
	s_movk_i32 s3, 0x84
	v_add3_u32 v24, v1, v3, v4
	v_or_b32_e32 v25, 8, v13
	v_or_b32_e32 v26, 16, v13
	v_or_b32_e32 v27, 24, v13
	s_movk_i32 s22, 0x80
	v_and_b32_e32 v28, 0x80, v81
	s_addc_u32 s9, s9, 0
	v_bfe_u32 v29, v67, 3, 2
	v_mov_b32_e32 v1, v6
	s_mov_b64 s[10:11], 0
	s_movk_i32 s23, 0xffc0
	s_mov_b32 s24, 0xffc0
	s_movk_i32 s25, 0x2c00
	s_movk_i32 s26, 0x63
	s_movk_i32 s27, 0x2400
	s_movk_i32 s28, 0x3ff
	s_movk_i32 s29, 0x700
	v_lshlrev_b32_e32 v14, 2, v2
	v_mov_b32_e32 v30, 1
	v_mov_b32_e32 v31, 6
	v_mov_b32_e32 v32, 5
	v_mov_b32_e32 v33, v80
	s_branch .Lt5_34

; __device__ __forceinline__ void prep_phase(const Params& p, LAS unsigned char* lds) {
;     ...
;         for (int it = gw; it < 2 * I_L; it += NGW) {
;             const int l = it / I_L; int r = it % I_L;
;             if (r < I_IN) { const int kb = r / 72, nb = r % 72; if (nb >= 48 && nb < 56) continue;
;                 transpose_item(p.w_in + (size_t)l * DM * INW_SRC, INW_SRC, DM, (bf16_t*)(ws + WS_WIN) + (size_t)l * INW * DM, 1, scr, kb, nb, lane); continue; }
.Lt5_33:
	s_or_b64 exec, exec, s[14:15]
	v_add_u32_e32 v33, s80, v33
	s_movk_i32 s12, 0xfff
	v_cmp_lt_i32_e32 vcc, s12, v33
	s_or_b64 s[10:11], vcc, s[10:11]
	s_andn2_b64 exec, exec, s[10:11]
	s_cbranch_execz .Lt5_76
.Lt5_34:
	s_mov_b32 s12, 0xb21642c9
	v_mul_hi_i32 v2, v33, s12
	v_add_u32_e32 v2, v2, v33
	v_lshrrev_b32_e32 v3, 31, v2
	v_ashrrev_i32_e32 v2, 12, v2
	v_add_u32_e32 v16, v2, v3
	v_mul_i32_i24_e32 v2, 0x1700, v16
	v_sub_u32_e32 v5, v33, v2
	s_movk_i32 s12, 0x47f
	v_cmp_lt_i32_e32 vcc, s12, v5
	s_and_saveexec_b64 s[12:13], vcc
	s_xor_b64 s[14:15], exec, s[12:13]
	s_cbranch_execz .Lt5_56

; __device__ __forceinline__ void prep_phase(const Params& p, LAS unsigned char* lds) {
;     ...
;             r -= I_IN;
;             if (r < I_OUT) { transpose_item(p.w_out + (size_t)l * DM * DM, DM, DM, (bf16_t*)(ws + WS_WOUT) + (size_t)l * DM * DM, 0, scr, r / 32, r % 32, lane); continue; }
;             r -= I_OUT;
	s_movk_i32 s12, 0x67f
	v_cmp_lt_u32_e32 vcc, s12, v5
	v_ashrrev_i32_e32 v17, 31, v16
	s_and_saveexec_b64 s[12:13], vcc
	s_xor_b64 s[16:17], exec, s[12:13]
	s_cbranch_execz .Lt5_51

; __device__ __forceinline__ void prep_phase(const Params& p, LAS unsigned char* lds) {
;     ...
;             r -= I_OUT;
;             if (r < I_F1) { transpose_item(p.w_ffn1 + (size_t)l * DM * DFF, DFF, DM, (bf16_t*)(ws + WS_W13) + (size_t)l * N13 * DM, 2, scr, r / 88, r % 88, lane); continue; }
;             r -= I_F1;
	s_movk_i32 s12, 0xbff
	v_cmp_lt_u32_e32 vcc, s12, v5
	s_mov_b32 s12, 0xb00000
	v_mad_i64_i32 v[2:3], s[12:13], v16, s12, 0
	s_and_saveexec_b64 s[12:13], vcc
	s_xor_b64 s[18:19], exec, s[12:13]
	s_cbranch_execz .Lt5_46

; __device__ __forceinline__ void prep_phase(const Params& p, LAS unsigned char* lds) {
;     ...
;             r -= I_F1;
;             if (r < I_F1) { transpose_item(p.w_ffn3 + (size_t)l * DM * DFF, DFF, DM, (bf16_t*)(ws + WS_W13) + (size_t)l * N13 * DM, 3, scr, r / 88, r % 88, lane); continue; }
;             r -= I_F1;
;             transpose_item(p.w_ffn2 + (size_t)l * DFF * DM, DM, DFF, (bf16_t*)(ws + WS_W2) + (size_t)l * DM * DFF, 0, scr, r / 32, r % 32, lane);
	s_movk_i32 s12, 0x117f
	v_cmp_lt_u32_e32 vcc, s12, v5
	s_and_saveexec_b64 s[12:13], vcc
	s_xor_b64 s[20:21], exec, s[12:13]
	s_cbranch_execz .Lt5_41

; #define LAS __attribute__((address_space(3)))
; __device__ __forceinline__ void transpose_item(const float* W, int ldw, int K, bf16_t* WT, int mode, LAS float* scr, int kb, int nb, int lane) {
;     const int k0 = 64 * kb, n0 = 32 * nb;
; #pragma unroll 8
;     for (int i = 0; i < 32; ++i) { const int kk = 2 * i + (lane >> 5); scr[kk * 33 + (lane & 31)] = W[(size_t)(k0 + kk) * ldw + n0 + (lane & 31)]; }
; __device__ __forceinline__ void prep_phase(const Params& p, LAS unsigned char* lds) {
;     ...
;             transpose_item(p.w_ffn2 + (size_t)l * DFF * DM, DM, DFF, (bf16_t*)(ws + WS_W2) + (size_t)l * DM * DFF, 0, scr, r / 32, r % 32, lane);
	v_readlane_b32 s36, v252, 48
	v_readlane_b32 s50, v252, 62
	v_readlane_b32 s51, v252, 63
	v_mov_b32_e32 v15, v9
	s_mov_b32 s30, 1
	v_lshl_add_u64 v[18:19], s[50:51], 0, v[2:3]
	v_lshlrev_b32_e32 v3, 5, v5
	v_lshlrev_b32_e32 v2, 1, v5
	v_and_b32_e32 v7, 0x3e0, v3
	v_and_b32_e32 v2, 0x7fffffc0, v2
	v_lshlrev_b32_e32 v8, 2, v7
	v_add_u32_e32 v2, 0xffffdd00, v2
	v_lshl_add_u64 v[4:5], v[18:19], 0, v[8:9]
	v_lshl_add_u64 v[4:5], v[4:5], 0, v[14:15]
	v_or_b32_e32 v3, v1, v2
	v_or_b32_e32 v8, v6, v2
	s_mov_b32 s31, 0
	s_mov_b32 s33, 32
	v_readlane_b32 s37, v252, 49
	v_readlane_b32 s38, v252, 50
	v_readlane_b32 s39, v252, 51
	v_readlane_b32 s40, v252, 52
	v_readlane_b32 s41, v252, 53
	v_readlane_b32 s42, v252, 54
	v_readlane_b32 s43, v252, 55
	v_readlane_b32 s44, v252, 56
	v_readlane_b32 s45, v252, 57
	v_readlane_b32 s46, v252, 58
	v_readlane_b32 s47, v252, 59
	v_readlane_b32 s48, v252, 60
	v_readlane_b32 s49, v252, 61

; #define LAS __attribute__((address_space(3)))
; __device__ __forceinline__ void prep_phase(const Params& p, LAS unsigned char* lds) {
;     ...
;         LAS float* scr = (LAS float*)(lds + wave * 8448);
;         constexpr int I_IN = 16 * 72, I_OUT = 16 * 32, I_F1 = 16 * 88, I_F2 = 44 * 32, I_L = I_IN + I_OUT + 2 * I_F1 + I_F2;
;         for (int it = gw; it < 2 * I_L; it += NGW) {
;             const int l = it / I_L; int r = it % I_L;
;             if (r < I_IN) { const int kb = r / 72, nb = r % 72; if (nb >= 48 && nb < 56) continue;
;                 transpose_item(p.w_in + (size_t)l * DM * INW_SRC, INW_SRC, DM, (bf16_t*)(ws + WS_WIN) + (size_t)l * INW * DM, 1, scr, kb, nb, lane); continue; }
;             r -= I_IN;
;             if (r < I_OUT) { transpose_item(p.w_out + (size_t)l * DM * DM, DM, DM, (bf16_t*)(ws + WS_WOUT) + (size_t)l * DM * DM, 0, scr, r / 32, r % 32, lane); continue; }
;             r -= I_OUT;
;             if (r < I_F1) { transpose_item(p.w_ffn1 + (size_t)l * DM * DFF, DFF, DM, (bf16_t*)(ws + WS_W13) + (size_t)l * N13 * DM, 2, scr, r / 88, r % 88, lane); continue; }
;             r -= I_F1;
;             if (r < I_F1) { transpose_item(p.w_ffn3 + (size_t)l * DM * DFF, DFF, DM, (bf16_t*)(ws + WS_W13) + (size_t)l * N13 * DM, 3, scr, r / 88, r % 88, lane); continue; }
;             r -= I_F1;
;             transpose_item(p.w_ffn2 + (size_t)l * DFF * DM, DM, DFF, (bf16_t*)(ws + WS_W2) + (size_t)l * DM * DFF, 0, scr, r / 32, r % 32, lane);
;         }
;     }
.Lt5_76:
	s_mov_b64 exec, -1
	v_readlane_b32 s3, v250, 0
	v_readlane_b32 s12, v250, 1
	v_readlane_b32 s13, v250, 2
	v_readlane_b32 s14, v250, 3
	v_readlane_b32 s16, v250, 4
	v_readlane_b32 s17, v250, 5
	v_readlane_b32 s18, v250, 6
	v_readlane_b32 s19, v250, 7
	v_readlane_b32 s21, v250, 8
	v_readlane_b32 s22, v250, 9
	v_readlane_b32 s23, v250, 10
	v_readlane_b32 s26, v250, 11
	v_readlane_b32 s27, v250, 12
	v_readlane_b32 s28, v250, 13
	v_readlane_b32 s29, v250, 14
	v_readlane_b32 s30, v250, 15
	v_readlane_b32 s33, v250, 16
	v_readlane_b32 s34, v250, 17
	v_readlane_b32 s35, v250, 18
	v_readlane_b32 s36, v250, 19
	v_readlane_b32 s37, v250, 20
	v_readlane_b32 s43, v250, 21
	v_readlane_b32 s44, v250, 22
	v_readlane_b32 s45, v250, 23
	v_readlane_b32 s46, v250, 24
	v_readlane_b32 s47, v250, 25
	v_readlane_b32 s48, v250, 26
	v_readlane_b32 s49, v250, 27
	v_readlane_b32 s50, v250, 28
	v_readlane_b32 s51, v250, 29
	v_readlane_b32 s52, v250, 30
	v_readlane_b32 s53, v250, 31
	v_readlane_b32 s54, v250, 32
	v_readlane_b32 s55, v250, 33
	v_readlane_b32 s56, v250, 34
	v_readlane_b32 s57, v250, 35
	v_readlane_b32 s64, v250, 36
	v_readlane_b32 s66, v250, 37
	v_readlane_b32 s67, v250, 38
	v_readlane_b32 s72, v250, 39
	v_readlane_b32 s73, v250, 40
	v_readlane_b32 s76, v250, 41
	v_readlane_b32 s80, v250, 42
	v_readlane_b32 s81, v250, 43
	v_readlane_b32 s84, v250, 44
	v_readlane_b32 s88, v250, 45
	v_readlane_b32 s89, v250, 46
	v_readlane_b32 s90, v250, 47
	v_readlane_b32 vcc_lo, v250, 48
	v_readlane_b32 vcc_hi, v250, 49
	v_readlane_b32 s0, v250, 50
	v_readlane_b32 s1, v250, 51
	s_nop 3
	s_mov_b64 exec, s[0:1]
